# NA attention: V tile global loads remapped so each instruction covers whole 128-B rows (8 lanes per row) instead of 32 partial rows - 4x fewer L1 line accesses
# speedup vs baseline: 1.0214x; 1.0141x over previous
; #define LAS __attribute__((address_space(3)))
; __device__ __forceinline__ void na_item(const bf16_t* __restrict__ PMIX, const bf16_t* __restrict__ GP, bf16_t* __restrict__ O, const float* __restrict__ bias, int item, int lane, LAS unsigned char* wl) {
;     const int q = lane & 31, hi = lane >> 5;
;     const bool lat = item < 8192;
;     int b, h, gi = 0, jh = 0, qrow;
;     if (lat) { b = item >> 11; h = (item >> 7) & 15; gi = (item >> 1) & 63; jh = item & 1; qrow = b * 4096 + gi * 64 + jh * 32 + q; }
;     else { const int it = item - 8192; b = it >> 7; h = (it >> 3) & 15; qrow = NLAT + b * 256 + (it & 7) * 32 + q; }
;     const int j = jh * 32 + q;
;     const int c0 = min(max(j - 8, 0), 48), r0 = min(max(gi - 4, 0), 56);
;     const bf16_t* qp = PMIX + (size_t)qrow * NMIXP + O_NAQ + h * 64 + hi * 8;
;     bf16x8 qf[4];
; #pragma unroll
;     for (int ks = 0; ks < 4; ++ks) qf[ks] = *reinterpret_cast<const bf16x8*>(qp + ks * 16);
;     f32x16 oT0 = {}, oT1 = {}; float m = -1e30f, l = 0.f;
;     const int ntiles = lat ? 24 : 8;
;     const float* bh = bias + h * (15 * 31);
;     LAS float* lbias = (LAS float*)(wl + 4608);
;     if (lat) {
; #pragma unroll
;         for (int i = 0; i < 4; ++i) { const int e = lane * 4 + i, krr = e >> 5, dc = e & 31; lbias[e] = bh[(r0 + krr - gi + 7) * 31 + min(dc, 30)] * LOG2E; }
;         asm volatile("s_waitcnt vmcnt(0) lgkmcnt(0)" ::: "memory"); __builtin_amdgcn_wave_barrier();
;     }
.Lna_norot:
	v_writelane_b32 v255, s34, 38
	s_and_b64 s[2:3], s[34:35], exec
	s_movk_i32 s1, 0x2200
	s_cselect_b32 s79, s1, 0x2000
	v_writelane_b32 v255, s35, 39
	s_cmp_ge_i32 s78, s79
	s_barrier
	s_cbranch_scc1 .LBB0_625
	s_lshl_b32 s80, s89, 3
	s_add_u32 s74, s90, 0x2087a000
	v_readlane_b32 s1, v255, 37
	s_addc_u32 s75, s1, 0
	s_add_u32 s2, s90, 0x2b27a000
	s_addc_u32 s3, s1, 0
	v_readlane_b32 s8, v254, 18
	s_add_u32 s4, s90, 0x572a6000
	v_readlane_b32 s6, v255, 20
	v_readlane_b32 s9, v254, 19
	v_readlane_b32 s10, v254, 20
	v_readlane_b32 s11, v254, 21
	v_readlane_b32 s12, v254, 22
	v_readlane_b32 s13, v254, 23
	v_readlane_b32 s16, v254, 26
	v_readlane_b32 s17, v254, 27
	s_addc_u32 s5, s1, 0
	s_mul_hi_u32 s1, s6, 0x7440
	s_mulk_i32 s6, 0x7440
	v_readlane_b32 s18, v254, 28
	v_readlane_b32 s19, v254, 29
	v_readlane_b32 s20, v254, 30
	v_readlane_b32 s21, v254, 31
	s_mov_b64 s[8:9], s[16:17]
	s_add_u32 s6, s8, s6
	s_mulk_i32 s0, 0x1600
	v_and_b32_e32 v0, 63, v176
	s_addc_u32 s82, s9, s1
	s_add_i32 s88, s0, 0
	v_bfe_u32 v1, v176, 5, 1
	v_lshlrev_b32_e32 v2, 2, v0
	v_mov_b32_e32 v3, s88
	v_bfe_u32 v167, v176, 3, 3
	s_movk_i32 s0, 0x90
	v_lshlrev_b32_e32 v168, 2, v1
	v_and_b32_e32 v128, 28, v2
	v_mad_u32_u24 v5, v167, s0, v3
	v_xor_b32_e32 v169, 0x80, v2
	v_or_b32_e32 v133, 8, v168
	v_lshlrev_b32_e32 v2, 4, v1
	v_mov_b32_e32 v3, v195
	v_or_b32_e32 v132, 32, v168
	v_lshl_add_u64 v[142:143], s[74:75], 0, v[2:3]
	v_lshlrev_b32_e32 v2, 1, v133
	v_and_b32_e32 v164, 31, v176
	v_lshl_add_u32 v166, v0, 4, s88
	v_or_b32_e32 v0, 3, v128
	v_and_b32_e32 v4, 1, v176
	v_or_b32_e32 v136, 40, v168
	v_lshl_add_u64 v[148:149], s[2:3], 0, v[2:3]
	v_lshl_add_u64 v[150:151], s[4:5], 0, v[2:3]
	v_lshlrev_b32_e32 v2, 1, v132
	v_lshlrev_b32_e32 v194, 3, v1
	v_min_u32_e32 v130, 30, v0
	v_lshlrev_b32_e32 v0, 5, v4
	v_lshlrev_b32_e32 v4, 6, v4
	v_lshl_add_u32 v6, v164, 1, s88
	v_mul_u32_u24_e32 v7, 0x240, v1
	v_mul_u32_u24_e32 v8, 0x90, v133
	v_lshl_add_u64 v[152:153], s[2:3], 0, v[2:3]
	v_lshl_add_u64 v[154:155], s[4:5], 0, v[2:3]
	v_lshlrev_b32_e32 v2, 1, v136
	v_readlane_b32 s7, v255, 21
	v_writelane_b32 v255, s6, 40
	v_bfe_u32 v165, v176, 3, 3
	v_or_b32_e32 v170, 16, v168
	v_or_b32_e32 v171, 17, v168
	v_or_b32_e32 v172, 18, v168
	v_or_b32_e32 v173, 19, v168
	v_or_b32_e32 v174, 24, v168
	v_or_b32_e32 v175, 25, v168
	v_or_b32_e32 v176, 26, v168
	v_or_b32_e32 v177, 27, v168
	v_or_b32_e32 v135, 33, v168
	v_or_b32_e32 v137, 35, v168
	v_or_b32_e32 v134, 34, v168
	v_or_b32_e32 v139, 41, v168
	v_or_b32_e32 v141, 43, v168
	v_or_b32_e32 v138, 42, v168
	v_mov_b32_e32 v129, v195
	v_mov_b32_e32 v131, v195
	v_lshl_add_u64 v[144:145], s[2:3], 0, v[194:195]
	v_lshl_add_u64 v[146:147], s[4:5], 0, v[194:195]
	v_lshl_add_u64 v[156:157], s[2:3], 0, v[2:3]
	v_lshl_add_u64 v[158:159], s[4:5], 0, v[2:3]
	v_or_b32_e32 v178, 0x48, v168
	v_add_u32_e32 v179, 0x47, v168
	v_or_b32_e32 v180, 0x42, v168
	v_or_b32_e32 v181, 0x41, v168
	v_or_b32_e32 v182, 64, v168
	v_add_u32_e32 v183, 63, v168
	v_lshlrev_b32_e32 v160, 1, v194
	v_and_b32_e32 v194, 7, v164
	v_lshlrev_b32_e32 v194, 4, v194
	v_add_u32_e32 v184, v5, v194
	s_mov_b64 s[98:99], 0x14000
	v_add_u32_e32 v185, v6, v7
	v_add_u32_e32 v186, v6, v8
	v_bfe_u32 v229, v164, 2, 2
	v_mul_u32_u24_e32 v229, 0x90, v229
	v_bfe_u32 v253, v164, 4, 1
	v_lshl_add_u32 v229, v253, 5, v229
	v_and_b32_e32 v253, 3, v164
	v_lshl_add_u32 v229, v253, 3, v229
	v_add_u32_e32 v229, v229, v7
	v_add_u32_e32 v229, s88, v229
	v_readlane_b32 s14, v254, 24
	v_readlane_b32 s15, v254, 25
	v_readlane_b32 s22, v254, 32
	v_readlane_b32 s23, v254, 33
	s_mov_b64 s[10:11], s[18:19]
	s_mov_b64 s[12:13], s[20:21]
	s_branch .LBB0_596

.LBB0_605:
	s_lshl_b32 s85, s6, 6
	v_add_u32_e32 v2, s8, v164
	v_mov_b64_e32 v[0:1], s[74:75]
	v_mad_i64_i32 v[2:3], s[2:3], v2, s71, v[0:1]
	s_lshl_b32 s72, s85, 1
	v_lshl_add_u64 v[2:3], v[2:3], 0, s[72:73]
	v_mov_b32_e32 v161, v195
	v_lshl_add_u64 v[2:3], v[2:3], 0, v[160:161]
	global_load_dwordx4 v[64:67], v[2:3], off offset:3712
	global_load_dwordx4 v[68:71], v[2:3], off offset:3744
	global_load_dwordx4 v[72:75], v[2:3], off offset:3776
	global_load_dwordx4 v[76:79], v[2:3], off offset:3808
	v_add_u32_e32 v2, s8, v167
	v_mad_i64_i32 v[0:1], s[2:3], v2, s71, v[0:1]
	v_lshl_add_u64 v[0:1], v[0:1], 0, s[72:73]
	v_lshl_add_u64 v[0:1], v[0:1], 0, v[194:195]
	s_mov_b64 s[2:3], 0x1680
	v_lshl_add_u64 v[2:3], v[0:1], 0, s[2:3]
	v_add_co_u32_e32 v0, vcc, 0x1000, v0
	s_mov_b64 s[2:3], -1
	s_nop 0
	v_addc_co_u32_e32 v1, vcc, 0, v1, vcc
	global_load_dwordx4 v[80:83], v[0:1], off offset:1664
	v_lshl_add_u64 v[92:93], v[2:3], 0, s[98:99]
	v_lshl_add_u64 v[88:89], v[92:93], 0, s[98:99]
	v_lshl_add_u64 v[84:85], v[88:89], 0, s[98:99]
	global_load_dwordx4 v[84:87], v[84:85], off
	global_load_dwordx4 v[88:91], v[88:89], off
	global_load_dwordx4 v[92:95], v[92:93], off
	s_and_b64 vcc, exec, s[0:1]
	s_cbranch_vccz .LBB0_607
	s_lshl_b32 s0, s4, 8
	s_add_i32 s1, s0, 0x4020
	s_lshl_b32 s66, s4, 12
	s_lshl_b32 s67, s5, 6
	s_mov_b64 s[2:3], 0

.LBB0_609:
	v_or_b32_e32 v0, s33, v164
	v_sub_u32_e64 v0, v0, 8 clamp
	v_min_u32_e32 v32, 48, v0
	v_add_u32_e32 v2, s1, v164
	v_mov_b64_e32 v[0:1], s[74:75]
	v_mad_i64_i32 v[2:3], s[2:3], v2, s71, v[0:1]
	v_lshl_add_u64 v[2:3], v[2:3], 0, s[72:73]
	v_mov_b32_e32 v161, v195
	v_lshl_add_u64 v[2:3], v[2:3], 0, v[160:161]
	global_load_dwordx4 v[96:99], v[2:3], off offset:3712
	global_load_dwordx4 v[100:103], v[2:3], off offset:3744
	global_load_dwordx4 v[104:107], v[2:3], off offset:3776
	global_load_dwordx4 v[108:111], v[2:3], off offset:3808
	v_add_u32_e32 v2, s1, v167
	v_mad_i64_i32 v[0:1], s[2:3], v2, s71, v[0:1]
	v_lshl_add_u64 v[0:1], v[0:1], 0, s[72:73]
	v_lshl_add_u64 v[0:1], v[0:1], 0, v[194:195]
	s_mov_b64 s[2:3], 0x1680
	v_lshl_add_u64 v[2:3], v[0:1], 0, s[2:3]
	v_add_co_u32_e32 v0, vcc, s96, v0
	v_cmp_lt_u32_e64 s[2:3], v168, v32
	s_nop 0
	v_addc_co_u32_e32 v1, vcc, 0, v1, vcc
	global_load_dwordx4 v[112:115], v[0:1], off offset:1664
	v_lshl_add_u64 v[124:125], v[2:3], 0, s[98:99]
	v_lshl_add_u64 v[120:121], v[124:125], 0, s[98:99]
	v_lshl_add_u64 v[116:117], v[120:121], 0, s[98:99]
	global_load_dwordx4 v[116:119], v[116:117], off
	global_load_dwordx4 v[120:123], v[120:121], off
	global_load_dwordx4 v[124:127], v[124:125], off
	v_or_b32_e32 v0, 1, v168
	v_cmp_lt_u32_e64 s[6:7], v0, v32
	v_or_b32_e32 v0, 3, v168
	v_or_b32_e32 v1, 2, v168
	v_cmp_lt_u32_e64 s[10:11], v0, v32
	v_or_b32_e32 v0, 9, v168
	v_cmp_lt_u32_e64 s[4:5], v1, v32
	v_or_b32_e32 v1, 10, v168
	v_cmp_lt_u32_e64 s[14:15], v0, v32
	v_or_b32_e32 v0, 11, v168
	v_cmp_lt_u32_e64 s[12:13], v1, v32
	v_cmp_lt_u32_e64 s[16:17], v0, v32
	v_add_u32_e32 v0, s33, v164
	v_or_b32_e32 v1, 0x4a, v168
	v_sub_u32_e32 v1, v1, v0
	v_min_u32_e32 v1, 30, v1
	v_lshlrev_b32_e32 v161, 2, v1
	v_or_b32_e32 v1, 0x49, v168
	v_sub_u32_e32 v1, v1, v0
	v_min_u32_e32 v1, 30, v1
	v_lshlrev_b32_e32 v188, 2, v1
	v_sub_u32_e32 v1, v178, v0
	v_min_u32_e32 v1, 30, v1
	v_lshlrev_b32_e32 v189, 2, v1
	v_sub_u32_e32 v1, v179, v0
	v_min_u32_e32 v1, 30, v1
	v_lshlrev_b32_e32 v190, 2, v1
	v_sub_u32_e32 v1, v180, v0
	v_min_u32_e32 v1, 30, v1
	v_lshlrev_b32_e32 v191, 2, v1
	v_sub_u32_e32 v1, v181, v0
	v_min_u32_e32 v1, 30, v1
	v_lshlrev_b32_e32 v192, 2, v1
	v_sub_u32_e32 v1, v182, v0
	v_min_u32_e32 v1, 30, v1
	v_lshlrev_b32_e32 v193, 2, v1
	v_sub_u32_e32 v1, v183, v0
	v_min_u32_e32 v1, 30, v1
	v_sub_u32_e32 v0, v168, v0
	v_lshlrev_b32_e32 v198, 2, v1
	v_max_i32_e32 v1, 0xffffffc6, v0
	v_add_u32_e32 v1, 58, v1
	v_min_u32_e32 v1, 30, v1
	v_lshlrev_b32_e32 v199, 2, v1
	v_max_i32_e32 v1, 0xffffffc7, v0
	v_add_u32_e32 v1, 57, v1
	v_min_u32_e32 v1, 30, v1
	v_lshlrev_b32_e32 v200, 2, v1
	v_max_i32_e32 v1, 0xffffffc8, v0
	v_add_u32_e32 v1, 56, v1
	v_min_u32_e32 v1, 30, v1
	v_lshlrev_b32_e32 v201, 2, v1
	v_max_i32_e32 v1, 0xffffffc9, v0
	v_add_u32_e32 v1, 55, v1
	v_min_u32_e32 v1, 30, v1
	v_lshlrev_b32_e32 v202, 2, v1
	v_max_i32_e32 v1, 0xffffffce, v0
	v_add_u32_e32 v1, 50, v1
	v_min_u32_e32 v1, 30, v1
	v_lshlrev_b32_e32 v203, 2, v1
	v_max_i32_e32 v1, 0xffffffcf, v0
	v_add_u32_e32 v1, 49, v1
	v_min_u32_e32 v1, 30, v1
	v_lshlrev_b32_e32 v204, 2, v1
	v_max_i32_e32 v1, 0xffffffd0, v0
	v_add_u32_e32 v1, 48, v1
	v_min_u32_e32 v1, 30, v1
	v_lshlrev_b32_e32 v205, 2, v1
	v_max_i32_e32 v1, 0xffffffd1, v0
	v_add_u32_e32 v1, 47, v1
	v_min_u32_e32 v1, 30, v1
	v_lshlrev_b32_e32 v206, 2, v1
	v_max_i32_e32 v1, 0xffffffd6, v0
	v_add_u32_e32 v1, 42, v1
	v_min_u32_e32 v1, 30, v1
	v_lshlrev_b32_e32 v207, 2, v1
	v_max_i32_e32 v1, 0xffffffd7, v0
	v_add_u32_e32 v1, 41, v1
	v_min_u32_e32 v1, 30, v1
	v_lshlrev_b32_e32 v208, 2, v1
	v_max_i32_e32 v1, 0xffffffd8, v0
	v_add_u32_e32 v1, 40, v1
	v_min_u32_e32 v1, 30, v1
	v_lshlrev_b32_e32 v209, 2, v1
	v_max_i32_e32 v1, 0xffffffd9, v0
	v_add_u32_e32 v1, 39, v1
	v_min_u32_e32 v1, 30, v1
	v_lshlrev_b32_e32 v210, 2, v1
	v_max_i32_e32 v1, 0xffffffde, v0
	v_add_u32_e32 v1, 34, v1
; #define LAS __attribute__((address_space(3)))
; __device__ __forceinline__ void na_item(const bf16_t* __restrict__ PMIX, const bf16_t* __restrict__ GP, bf16_t* __restrict__ O, const float* __restrict__ bias, int item, int lane, LAS unsigned char* wl) {
;     ...
;     const int c0 = min(max(j - 8, 0), 48), r0 = min(max(gi - 4, 0), 56);
;     const bf16_t* qp = PMIX + (size_t)qrow * NMIXP + O_NAQ + h * 64 + hi * 8;
;     bf16x8 qf[4];
; #pragma unroll
;     for (int ks = 0; ks < 4; ++ks) qf[ks] = *reinterpret_cast<const bf16x8*>(qp + ks * 16);
;     f32x16 oT0 = {}, oT1 = {}; float m = -1e30f, l = 0.f;
;     const int ntiles = lat ? 24 : 8;
;     const float* bh = bias + h * (15 * 31);
;     LAS float* lbias = (LAS float*)(wl + 4608);
;     if (lat) {
; #pragma unroll
;         for (int i = 0; i < 4; ++i) { const int e = lane * 4 + i, krr = e >> 5, dc = e & 31; lbias[e] = bh[(r0 + krr - gi + 7) * 31 + min(dc, 30)] * LOG2E; }
;         asm volatile("s_waitcnt vmcnt(0) lgkmcnt(0)" ::: "memory"); __builtin_amdgcn_wave_barrier();
;     }
	v_add_u32_e32 v2, 16, v32
	v_cmp_ge_u32_e32 vcc, v170, v32
	v_min_u32_e32 v1, 30, v1
	s_add_i32 s86, s0, 0x4000
	s_and_b64 s[18:19], vcc, s[2:3]
	v_cmp_ge_u32_e32 vcc, v171, v32
	v_cmp_lt_u32_e64 s[0:1], v171, v2
	v_lshlrev_b32_e32 v211, 2, v1
	v_max_i32_e32 v1, 0xffffffdf, v0
	s_and_b64 s[20:21], vcc, s[0:1]
	v_cmp_ge_u32_e32 vcc, v172, v32
	v_cmp_lt_u32_e64 s[0:1], v172, v2
	v_add_u32_e32 v1, 33, v1
	s_and_b64 s[22:23], vcc, s[0:1]
	v_cmp_ge_u32_e32 vcc, v173, v32
	v_cmp_lt_u32_e64 s[0:1], v173, v2
	v_min_u32_e32 v1, 30, v1
	s_and_b64 s[24:25], vcc, s[0:1]
	v_cmp_ge_u32_e32 vcc, v174, v32
	v_cmp_lt_u32_e64 s[0:1], v174, v2
	v_lshlrev_b32_e32 v212, 2, v1
	v_max_i32_e32 v1, 0xffffffe0, v0
	s_and_b64 s[26:27], vcc, s[0:1]
	v_cmp_ge_u32_e32 vcc, v175, v32
	v_cmp_lt_u32_e64 s[0:1], v175, v2
	v_add_u32_e32 v1, 32, v1
	s_and_b64 s[28:29], vcc, s[0:1]
	v_cmp_ge_u32_e32 vcc, v176, v32
	v_cmp_lt_u32_e64 s[0:1], v176, v2
	v_min_u32_e32 v1, 30, v1
	s_and_b64 s[30:31], vcc, s[0:1]
	v_cmp_ge_u32_e32 vcc, v177, v32
	v_cmp_lt_u32_e64 s[0:1], v177, v2
	v_lshlrev_b32_e32 v213, 2, v1
	v_max_i32_e32 v1, 0xffffffe1, v0
	s_and_b64 s[34:35], vcc, s[0:1]
	v_cmp_ge_u32_e32 vcc, v132, v32
	v_cmp_lt_u32_e64 s[0:1], v170, v32
	v_add_u32_e32 v1, 31, v1
	s_and_b64 s[36:37], vcc, s[0:1]
	v_cmp_ge_u32_e32 vcc, v135, v32
	v_cmp_lt_u32_e64 s[0:1], v171, v32
	v_min_u32_e32 v1, 30, v1
	s_and_b64 s[38:39], vcc, s[0:1]
	v_cmp_ge_u32_e32 vcc, v134, v32
	v_cmp_lt_u32_e64 s[0:1], v172, v32
	v_lshlrev_b32_e32 v214, 2, v1
	v_max_i32_e32 v1, 0xffffffe6, v0
	s_and_b64 s[40:41], vcc, s[0:1]
	v_cmp_ge_u32_e32 vcc, v137, v32
	v_cmp_lt_u32_e64 s[0:1], v173, v32
	v_lshlrev_b32_e32 v215, 2, v1
	v_max_i32_e32 v1, 0xffffffe7, v0
	s_and_b64 s[42:43], vcc, s[0:1]
	v_cmp_ge_u32_e32 vcc, v136, v32
	v_cmp_lt_u32_e64 s[0:1], v174, v32
	v_lshlrev_b32_e32 v216, 2, v1
	v_max_i32_e32 v1, 0xffffffe8, v0
	s_and_b64 s[54:55], vcc, s[0:1]
	v_cmp_ge_u32_e32 vcc, v139, v32
	v_cmp_lt_u32_e64 s[0:1], v175, v32
	v_lshlrev_b32_e32 v217, 2, v1
	v_max_i32_e32 v1, 0xffffffe9, v0
	s_and_b64 s[56:57], vcc, s[0:1]
	v_cmp_ge_u32_e32 vcc, v138, v32
	v_cmp_lt_u32_e64 s[0:1], v176, v32
	v_lshlrev_b32_e32 v218, 2, v1
	v_max_i32_e32 v1, 0xffffffee, v0
	s_and_b64 s[58:59], vcc, s[0:1]
	v_cmp_ge_u32_e32 vcc, v141, v32
	v_cmp_lt_u32_e64 s[0:1], v177, v32
	v_lshlrev_b32_e32 v219, 2, v1
	v_max_i32_e32 v1, 0xffffffef, v0
	s_and_b64 s[60:61], vcc, s[0:1]
	v_lshlrev_b32_e32 v220, 2, v1
	v_max_i32_e32 v1, -16, v0
	v_max_i32_e32 v0, -15, v0
	s_add_i32 s0, s66, s67
	v_mov_b32_e32 v232, 0
	v_cmp_lt_u32_e64 s[8:9], v133, v32
	v_cmp_lt_u32_e64 s[44:45], v135, v32
	v_cmp_lt_u32_e64 s[46:47], v132, v32
	v_cmp_lt_u32_e64 s[48:49], v137, v32
	v_cmp_lt_u32_e64 s[50:51], v134, v32
	v_cmp_lt_u32_e64 s[52:53], v139, v32
	v_cmp_lt_u32_e64 s[62:63], v136, v32
	v_cmp_lt_u32_e64 s[64:65], v141, v32
	v_lshl_add_u64 v[162:163], v[142:143], 0, s[72:73]
	v_lshlrev_b32_e32 v221, 2, v1
	v_lshlrev_b32_e32 v231, 2, v0
	s_add_i32 s87, s0, 0x60
	v_mov_b32_e32 v140, 0xf149f2ca
	s_mov_b32 s93, -14
	v_mov_b32_e32 v16, 0
	v_mov_b32_e32 v17, v232
	v_mov_b32_e32 v18, v232
	v_mov_b32_e32 v19, v232
	v_mov_b32_e32 v20, v232
	v_mov_b32_e32 v21, v232
	v_mov_b32_e32 v22, v232
	v_mov_b32_e32 v23, v232
	v_mov_b32_e32 v24, v232
	v_mov_b32_e32 v25, v232
	v_mov_b32_e32 v26, v232
	v_mov_b32_e32 v27, v232
	v_mov_b32_e32 v28, v232
	v_mov_b32_e32 v29, v232
	v_mov_b32_e32 v30, v232
	v_mov_b32_e32 v31, v232
	v_mov_b32_e32 v0, 0
	v_mov_b32_e32 v1, v232
	v_mov_b32_e32 v2, v232
	v_mov_b32_e32 v3, v232
	v_mov_b32_e32 v4, v232
	v_mov_b32_e32 v5, v232
	v_mov_b32_e32 v6, v232
	v_mov_b32_e32 v7, v232
	v_mov_b32_e32 v8, v232
	v_mov_b32_e32 v9, v232
	v_mov_b32_e32 v10, v232
	v_mov_b32_e32 v11, v232
	v_mov_b32_e32 v12, v232
	v_mov_b32_e32 v13, v232
	v_mov_b32_e32 v14, v232
	v_mov_b32_e32 v15, v232
	s_mov_b32 s83, s88
	v_cmp_lt_u32_e64 s[66:67], v138, v32
	s_branch .LBB0_611

.LBB0_611:
	s_waitcnt vmcnt(15)
	v_mfma_f32_32x32x16_bf16 v[32:47], v[64:67], v[48:51], 0
	s_add_i32 s81, s93, 14
	s_add_i32 s33, s93, 16
	s_cmp_ge_u32 s33, s84
	s_waitcnt vmcnt(11)
	ds_write_b128 v184, v[80:83]
	s_waitcnt vmcnt(8)
	ds_write_b128 v184, v[92:95] offset:1152
	ds_write_b128 v184, v[88:91] offset:2304
	ds_write_b128 v184, v[84:87] offset:3456
	v_mfma_f32_32x32x16_bf16 v[32:47], v[68:71], v[52:55], v[32:47]
	v_mfma_f32_32x32x16_bf16 v[32:47], v[72:75], v[56:59], v[32:47]
	v_mfma_f32_32x32x16_bf16 v[32:47], v[76:79], v[60:63], v[32:47]
	s_cbranch_scc1 .LBB0_617
	s_cmp_lt_u32 s81, 14
	s_cselect_b64 s[0:1], -1, 0
	s_and_b64 s[0:1], s[76:77], s[0:1]
	s_andn2_b64 vcc, exec, s[0:1]
	s_mov_b64 s[0:1], -1
	s_cbranch_vccz .LBB0_614
	s_and_b64 s[0:1], s[76:77], exec
	s_cselect_b32 s0, s93, s33
	s_lshl_b32 s0, s0, 5
	s_add_i32 s68, s0, s86
	s_mov_b64 s[0:1], 0

.LBB0_616:
	v_add_u32_e32 v82, s68, v167
	v_mov_b64_e32 v[80:81], s[74:75]
	v_add_u32_e32 v64, s68, v164
	v_mad_i64_i32 v[80:81], s[0:1], v82, s71, v[80:81]
	v_mad_i64_i32 v[76:77], s[0:1], v64, s71, v[162:163]
	v_lshl_add_u64 v[80:81], v[80:81], 0, s[72:73]
	v_lshl_add_u64 v[80:81], v[80:81], 0, v[194:195]
	s_mov_b64 s[0:1], 0x1680
	v_lshl_add_u64 v[92:93], v[80:81], 0, s[0:1]
	v_add_co_u32_e32 v80, vcc, s96, v80
	global_load_dwordx4 v[64:67], v[76:77], off offset:3712
	global_load_dwordx4 v[68:71], v[76:77], off offset:3744
	global_load_dwordx4 v[72:75], v[76:77], off offset:3776
	s_nop 0
	global_load_dwordx4 v[76:79], v[76:77], off offset:3808
	v_addc_co_u32_e32 v81, vcc, 0, v81, vcc
	global_load_dwordx4 v[80:83], v[80:81], off offset:1664
	s_nop 0
	v_lshl_add_u64 v[92:93], v[92:93], 0, s[98:99]
	v_lshl_add_u64 v[88:89], v[92:93], 0, s[98:99]
	v_lshl_add_u64 v[84:85], v[88:89], 0, s[98:99]
	global_load_dwordx4 v[84:87], v[84:85], off
	global_load_dwordx4 v[88:91], v[88:89], off
	global_load_dwordx4 v[92:95], v[92:93], off

.LBB0_619:
	s_nop 3
	v_max_f32_e32 v222, v33, v33
	v_max_f32_e32 v223, v32, v32
	v_max_f32_e32 v222, v223, v222
	v_max3_f32 v222, v222, v34, v35
	v_max3_f32 v222, v222, v36, v37
	v_max3_f32 v222, v222, v38, v39
	v_max3_f32 v222, v222, v40, v41
	v_max3_f32 v222, v222, v42, v43
	v_max3_f32 v222, v222, v44, v45
	v_max3_f32 v222, v222, v46, v47
	ds_bpermute_b32 v223, v169, v222
	s_waitcnt lgkmcnt(0)
	s_add_i32 s0, s93, 17
	s_cmp_ge_u32 s0, s84
	s_waitcnt lgkmcnt(0)
	v_max3_f32 v233, v140, v222, v223
	v_sub_f32_e32 v32, v32, v233
	v_exp_f32_e32 v234, v32
	v_sub_f32_e32 v32, v33, v233
	v_exp_f32_e32 v235, v32
	v_sub_f32_e32 v32, v34, v233
	v_exp_f32_e32 v236, v32
	v_sub_f32_e32 v32, v35, v233
	v_exp_f32_e32 v237, v32
	v_sub_f32_e32 v32, v36, v233
	v_exp_f32_e32 v238, v32
	v_sub_f32_e32 v32, v37, v233
	v_exp_f32_e32 v239, v32
	v_sub_f32_e32 v32, v38, v233
	v_exp_f32_e32 v240, v32
	v_sub_f32_e32 v32, v39, v233
	v_exp_f32_e32 v241, v32
	v_sub_f32_e32 v32, v40, v233
	v_exp_f32_e32 v242, v32
	v_sub_f32_e32 v32, v41, v233
	v_exp_f32_e32 v243, v32
	v_sub_f32_e32 v32, v42, v233
	v_exp_f32_e32 v244, v32
	v_sub_f32_e32 v32, v43, v233
	ds_read_b64_tr_b16 v[36:37], v229
	ds_read_b64_tr_b16 v[38:39], v229 offset:1152
	v_sub_f32_e32 v140, v140, v233
	v_exp_f32_e32 v245, v32
	v_sub_f32_e32 v32, v44, v233
	v_exp_f32_e32 v140, v140
	s_waitcnt lgkmcnt(2)
	s_waitcnt lgkmcnt(0)
	v_exp_f32_e32 v246, v32
	v_sub_f32_e32 v32, v45, v233
	v_exp_f32_e32 v247, v32
	v_sub_f32_e32 v32, v46, v233
	v_exp_f32_e32 v248, v32
	v_sub_f32_e32 v32, v47, v233
	v_exp_f32_e32 v249, v32
	v_cvt_pk_bf16_f32 v32, v234, v235
	v_cvt_pk_bf16_f32 v33, v236, v237
	v_cvt_pk_bf16_f32 v34, v238, v239
	v_cvt_pk_bf16_f32 v35, v240, v241
	v_pk_mul_f32 v[30:31], v[30:31], v[140:141] op_sel_hi:[1,0]
	v_pk_mul_f32 v[28:29], v[28:29], v[140:141] op_sel_hi:[1,0]
	v_pk_mul_f32 v[26:27], v[26:27], v[140:141] op_sel_hi:[1,0]
	v_pk_mul_f32 v[24:25], v[24:25], v[140:141] op_sel_hi:[1,0]
	v_pk_mul_f32 v[22:23], v[22:23], v[140:141] op_sel_hi:[1,0]
	v_pk_mul_f32 v[20:21], v[20:21], v[140:141] op_sel_hi:[1,0]
	v_pk_mul_f32 v[18:19], v[18:19], v[140:141] op_sel_hi:[1,0]
	v_pk_mul_f32 v[16:17], v[16:17], v[140:141] op_sel_hi:[1,0]
	v_pk_mul_f32 v[14:15], v[14:15], v[140:141] op_sel_hi:[1,0]
	v_pk_mul_f32 v[12:13], v[12:13], v[140:141] op_sel_hi:[1,0]
	v_mfma_f32_32x32x16_bf16 v[16:31], v[36:39], v[32:35], v[16:31]
	ds_read_b64_tr_b16 v[36:37], v229 offset:64
	ds_read_b64_tr_b16 v[38:39], v229 offset:1216
	s_waitcnt lgkmcnt(2)
	v_pk_mul_f32 v[10:11], v[10:11], v[140:141] op_sel_hi:[1,0]
	s_waitcnt lgkmcnt(0)
	v_pk_mul_f32 v[8:9], v[8:9], v[140:141] op_sel_hi:[1,0]
	v_pk_mul_f32 v[6:7], v[6:7], v[140:141] op_sel_hi:[1,0]
	v_pk_mul_f32 v[4:5], v[4:5], v[140:141] op_sel_hi:[1,0]
	v_pk_mul_f32 v[2:3], v[2:3], v[140:141] op_sel_hi:[1,0]
	v_pk_mul_f32 v[0:1], v[0:1], v[140:141] op_sel_hi:[1,0]
	s_nop 1
	v_mfma_f32_32x32x16_bf16 v[0:15], v[36:39], v[32:35], v[0:15]
	ds_read_b64_tr_b16 v[36:37], v229 offset:2304
	ds_read_b64_tr_b16 v[38:39], v229 offset:3456
	s_waitcnt lgkmcnt(2)
	v_cvt_pk_bf16_f32 v32, v242, v243
	s_waitcnt lgkmcnt(0)
	v_cvt_pk_bf16_f32 v33, v244, v245
	v_cvt_pk_bf16_f32 v34, v246, v247
	v_cvt_pk_bf16_f32 v35, v248, v249
	s_nop 1
	v_mfma_f32_32x32x16_bf16 v[16:31], v[36:39], v[32:35], v[16:31]
	ds_read_b64_tr_b16 v[36:37], v229 offset:2368
	ds_read_b64_tr_b16 v[38:39], v229 offset:3520
	s_waitcnt lgkmcnt(2)
	s_waitcnt lgkmcnt(0)
	s_waitcnt vmcnt(3)
	ds_write_b128 v184, v[112:115]
	s_waitcnt vmcnt(0)
	ds_write_b128 v184, v[124:127] offset:1152
	ds_write_b128 v184, v[120:123] offset:2304
	ds_write_b128 v184, v[116:119] offset:3456
	v_mfma_f32_32x32x16_bf16 v[0:15], v[36:39], v[32:35], v[0:15]
	v_mfma_f32_32x32x16_bf16 v[32:47], v[96:99], v[48:51], 0
	v_mfma_f32_32x32x16_bf16 v[32:47], v[100:103], v[52:55], v[32:47]
	v_mfma_f32_32x32x16_bf16 v[32:47], v[104:107], v[56:59], v[32:47]
	v_mfma_f32_32x32x16_bf16 v[32:47], v[108:111], v[60:63], v[32:47]
	s_cbranch_scc1 .LBB0_623
	s_cmp_lt_u32 s81, 13
	s_cselect_b64 vcc, -1, 0
	s_and_b64 vcc, s[76:77], vcc
	s_and_b64 vcc, exec, vcc
	s_mov_b32 s1, s87
	s_cbranch_vccnz .LBB0_622
	s_add_i32 s1, s93, 1
	s_and_b64 vcc, s[76:77], exec
	s_cselect_b32 s0, s1, s0
	s_lshl_b32 s0, s0, 5
	s_add_i32 s1, s0, s86
.LBB0_622:
	v_add_u32_e32 v114, s1, v167
	v_mov_b64_e32 v[112:113], s[74:75]
	v_add_u32_e32 v96, s1, v164
	v_mad_i64_i32 v[112:113], s[0:1], v114, s71, v[112:113]
	v_lshl_add_u64 v[112:113], v[112:113], 0, s[72:73]
	v_mad_i64_i32 v[108:109], vcc, v96, s71, v[162:163]
	v_lshl_add_u64 v[112:113], v[112:113], 0, v[194:195]
	s_mov_b64 s[0:1], 0x1680
	v_lshl_add_u64 v[124:125], v[112:113], 0, s[0:1]
	v_add_co_u32_e32 v112, vcc, s96, v112
	global_load_dwordx4 v[96:99], v[108:109], off offset:3712
	global_load_dwordx4 v[100:103], v[108:109], off offset:3744
	global_load_dwordx4 v[104:107], v[108:109], off offset:3776
	s_nop 0
	global_load_dwordx4 v[108:111], v[108:109], off offset:3808
	v_addc_co_u32_e32 v113, vcc, 0, v113, vcc
	global_load_dwordx4 v[112:115], v[112:113], off offset:1664
	s_nop 0
	v_lshl_add_u64 v[124:125], v[124:125], 0, s[98:99]
	v_lshl_add_u64 v[120:121], v[124:125], 0, s[98:99]
	v_lshl_add_u64 v[116:117], v[120:121], 0, s[98:99]
	global_load_dwordx4 v[116:119], v[116:117], off
	global_load_dwordx4 v[120:123], v[120:121], off
	global_load_dwordx4 v[124:127], v[124:125], off
